# GEMM kinds 2/3 bf16 epilogue hand-written (row offsets by adds, paired cvt, short stores) instead of three integer multiplies per element; epilogues drain their stores before the wave can reach the gr
# speedup vs baseline: 1.2514x; 1.0078x over previous
.LBB0_943:
	s_and_b32 s12, s5, 64
	s_mulk_i32 s12, 0x90
	v_add_u32_e32 v148, s12, v237
	ds_read_b128 v[192:195], v148
	ds_read_b128 v[196:199], v148 offset:32
	ds_read_b128 v[200:203], v148 offset:64
	ds_read_b128 v[204:207], v148 offset:96
	s_addk_i32 s12, 0x4800
	v_add_u32_e32 v149, s12, v238
	s_addk_i32 s12, 0x1200
	v_add_u32_e32 v150, s12, v238
	v_lshl_add_u64 v[102:103], v[144:145], 0, v[16:17]
	global_load_dwordx4 v[102:105], v[102:103], off
	v_lshl_add_u64 v[106:107], v[140:141], 0, v[16:17]
	global_load_dwordx4 v[106:109], v[106:107], off
	v_lshl_add_u64 v[110:111], v[142:143], 0, v[16:17]
	global_load_dwordx4 v[110:113], v[110:111], off
	v_lshl_add_u64 v[114:115], v[138:139], 0, v[16:17]
	global_load_dwordx4 v[114:117], v[114:115], off
	s_waitcnt vmcnt(4)
	s_add_i32 s5, s5, 64
	s_waitcnt lgkmcnt(3)
	v_mfma_f32_32x32x16_bf16 v[152:167], v[192:195], v[18:21], v[0:15]
	ds_read2_b64 v[212:215], v149 offset1:2
	s_waitcnt lgkmcnt(3)
	v_mfma_f32_32x32x16_bf16 v[152:167], v[196:199], v[22:25], v[152:167]
	ds_read2_b64 v[220:223], v150 offset1:2
	s_waitcnt lgkmcnt(3)
	v_mfma_f32_32x32x16_bf16 v[152:167], v[200:203], v[26:29], v[152:167]
	ds_read2_b64 v[216:219], v149 offset0:4 offset1:6
	s_waitcnt lgkmcnt(3)
	v_mfma_f32_32x32x16_bf16 v[152:167], v[204:207], v[30:33], v[152:167]
	ds_read2_b64 v[244:247], v150 offset0:4 offset1:6
	v_lshl_add_u64 v[138:139], v[138:139], 0, s[66:67]
	v_lshl_add_u64 v[140:141], v[140:141], 0, s[66:67]
	v_lshl_add_u64 v[142:143], v[142:143], 0, s[68:69]
	v_lshl_add_u64 v[144:145], v[144:145], 0, s[68:69]
	v_mfma_f32_32x32x16_bf16 v[168:183], v[192:195], v[34:37], v[0:15]
	ds_read_b128 v[192:195], v148 offset:4608
	v_mfma_f32_32x32x16_bf16 v[168:183], v[196:199], v[130:133], v[168:183]
	ds_read_b128 v[196:199], v148 offset:4640
	v_mfma_f32_32x32x16_bf16 v[168:183], v[200:203], v[134:137], v[168:183]
	ds_read_b128 v[200:203], v148 offset:4672
	v_mfma_f32_32x32x16_bf16 v[168:183], v[204:207], v[248:251], v[168:183]
	ds_read_b128 v[204:207], v148 offset:4704
	v_exp_f32_e32 v152, v152
	v_exp_f32_e32 v153, v153
	v_exp_f32_e32 v154, v154
	v_exp_f32_e32 v155, v155
	v_exp_f32_e32 v156, v156
	v_exp_f32_e32 v157, v157
	v_exp_f32_e32 v158, v158
	v_exp_f32_e32 v159, v159
	v_exp_f32_e32 v160, v160
	v_exp_f32_e32 v161, v161
	v_exp_f32_e32 v162, v162
	v_exp_f32_e32 v163, v163
	v_exp_f32_e32 v164, v164
	v_exp_f32_e32 v165, v165
	v_exp_f32_e32 v166, v166
	v_exp_f32_e32 v167, v167
	v_cvt_pk_bf16_f32 v184, v152, v153
	v_cvt_pk_bf16_f32 v185, v154, v155
	v_cvt_pk_bf16_f32 v186, v156, v157
	v_cvt_pk_bf16_f32 v187, v158, v159
	v_cvt_pk_bf16_f32 v188, v160, v161
	v_cvt_pk_bf16_f32 v189, v162, v163
	v_cvt_pk_bf16_f32 v190, v164, v165
	v_cvt_pk_bf16_f32 v191, v166, v167
	v_add_f32_e32 v152, v152, v153
	v_add_f32_e32 v154, v154, v155
	v_add_f32_e32 v156, v156, v157
	v_add_f32_e32 v158, v158, v159
	v_add_f32_e32 v160, v160, v161
	v_add_f32_e32 v162, v162, v163
	v_add_f32_e32 v164, v164, v165
	v_add_f32_e32 v166, v166, v167
	v_add_f32_e32 v152, v152, v154
	v_add_f32_e32 v156, v156, v158
	v_add_f32_e32 v160, v160, v162
	v_add_f32_e32 v164, v164, v166
	v_add_f32_e32 v152, v152, v156
	v_add_f32_e32 v160, v160, v164
	v_add_f32_e32 v152, v152, v160
	v_add_f32_e32 v146, v146, v152
	s_waitcnt lgkmcnt(7)
	v_mfma_f32_32x32x16_bf16 v[38:53], v[212:215], v[184:187], v[38:53]
	v_exp_f32_e32 v168, v168
	v_exp_f32_e32 v169, v169
	v_exp_f32_e32 v170, v170
	v_exp_f32_e32 v171, v171
	s_waitcnt lgkmcnt(6)
	v_mfma_f32_32x32x16_bf16 v[70:85], v[220:223], v[184:187], v[70:85]
	v_exp_f32_e32 v172, v172
	v_exp_f32_e32 v173, v173
	v_exp_f32_e32 v174, v174
	v_exp_f32_e32 v175, v175
	s_waitcnt lgkmcnt(5)
	v_mfma_f32_32x32x16_bf16 v[38:53], v[216:219], v[188:191], v[38:53]
	v_exp_f32_e32 v176, v176
	v_exp_f32_e32 v177, v177
	v_exp_f32_e32 v178, v178
	v_exp_f32_e32 v179, v179
	s_waitcnt lgkmcnt(4)
	v_mfma_f32_32x32x16_bf16 v[70:85], v[244:247], v[188:191], v[70:85]
	v_exp_f32_e32 v180, v180
	v_exp_f32_e32 v181, v181
	v_exp_f32_e32 v182, v182
	v_exp_f32_e32 v183, v183
	v_cvt_pk_bf16_f32 v184, v168, v169
	s_waitcnt lgkmcnt(3)
	v_mfma_f32_32x32x16_bf16 v[152:167], v[192:195], v[18:21], v[0:15]
	v_cvt_pk_bf16_f32 v185, v170, v171
	v_cvt_pk_bf16_f32 v186, v172, v173
	v_cvt_pk_bf16_f32 v187, v174, v175
	v_cvt_pk_bf16_f32 v188, v176, v177
	s_waitcnt lgkmcnt(2)
	v_mfma_f32_32x32x16_bf16 v[152:167], v[196:199], v[22:25], v[152:167]
	v_cvt_pk_bf16_f32 v189, v178, v179
	v_cvt_pk_bf16_f32 v190, v180, v181
	v_cvt_pk_bf16_f32 v191, v182, v183
	v_add_f32_e32 v168, v168, v169
	s_waitcnt lgkmcnt(1)
	v_mfma_f32_32x32x16_bf16 v[152:167], v[200:203], v[26:29], v[152:167]
	v_add_f32_e32 v170, v170, v171
	v_add_f32_e32 v172, v172, v173
	v_add_f32_e32 v174, v174, v175
	v_add_f32_e32 v176, v176, v177
	s_waitcnt lgkmcnt(0)
	v_mfma_f32_32x32x16_bf16 v[152:167], v[204:207], v[30:33], v[152:167]
	v_add_f32_e32 v178, v178, v179
	v_add_f32_e32 v180, v180, v181
	v_add_f32_e32 v182, v182, v183
	v_add_f32_e32 v168, v168, v170
	v_add_f32_e32 v172, v172, v174
	v_add_f32_e32 v176, v176, v178
	v_add_f32_e32 v180, v180, v182
	v_add_f32_e32 v168, v168, v172
	v_add_f32_e32 v176, v176, v180
	v_add_f32_e32 v168, v168, v176
	v_add_f32_e32 v147, v147, v168
	v_mfma_f32_32x32x16_bf16 v[54:69], v[212:215], v[184:187], v[54:69]
	ds_read2_b64 v[212:215], v149 offset0:8 offset1:10
	v_exp_f32_e32 v152, v152
	v_exp_f32_e32 v153, v153
	v_exp_f32_e32 v154, v154
	v_exp_f32_e32 v155, v155
	v_mfma_f32_32x32x16_bf16 v[86:101], v[220:223], v[184:187], v[86:101]
	ds_read2_b64 v[220:223], v150 offset0:8 offset1:10
	v_exp_f32_e32 v156, v156
	v_exp_f32_e32 v157, v157
	v_exp_f32_e32 v158, v158
	v_exp_f32_e32 v159, v159
	v_mfma_f32_32x32x16_bf16 v[54:69], v[216:219], v[188:191], v[54:69]
	ds_read2_b64 v[216:219], v149 offset0:12 offset1:14
	v_exp_f32_e32 v160, v160
	v_exp_f32_e32 v161, v161
	v_exp_f32_e32 v162, v162
	v_exp_f32_e32 v163, v163
	v_mfma_f32_32x32x16_bf16 v[86:101], v[244:247], v[188:191], v[86:101]
	ds_read2_b64 v[244:247], v150 offset0:12 offset1:14
	v_exp_f32_e32 v164, v164
	v_exp_f32_e32 v165, v165
	v_exp_f32_e32 v166, v166
	v_exp_f32_e32 v167, v167
	v_cvt_pk_bf16_f32 v184, v152, v153
	v_mfma_f32_32x32x16_bf16 v[168:183], v[192:195], v[34:37], v[0:15]
	v_cvt_pk_bf16_f32 v185, v154, v155
	v_cvt_pk_bf16_f32 v186, v156, v157
	v_cvt_pk_bf16_f32 v187, v158, v159
	v_cvt_pk_bf16_f32 v188, v160, v161
	v_mfma_f32_32x32x16_bf16 v[168:183], v[196:199], v[130:133], v[168:183]
	v_cvt_pk_bf16_f32 v189, v162, v163
	v_cvt_pk_bf16_f32 v190, v164, v165
	v_cvt_pk_bf16_f32 v191, v166, v167
	v_add_f32_e32 v152, v152, v153
	v_mfma_f32_32x32x16_bf16 v[168:183], v[200:203], v[134:137], v[168:183]
	v_add_f32_e32 v154, v154, v155
	v_add_f32_e32 v156, v156, v157
	v_add_f32_e32 v158, v158, v159
	v_add_f32_e32 v160, v160, v161
	v_mfma_f32_32x32x16_bf16 v[168:183], v[204:207], v[248:251], v[168:183]
	v_add_f32_e32 v162, v162, v163
	v_add_f32_e32 v164, v164, v165
	v_add_f32_e32 v166, v166, v167
	v_add_f32_e32 v152, v152, v154
	v_add_f32_e32 v156, v156, v158
	v_add_f32_e32 v160, v160, v162
	v_add_f32_e32 v164, v164, v166
	v_add_f32_e32 v152, v152, v156
	v_add_f32_e32 v160, v160, v164
	v_add_f32_e32 v152, v152, v160
	v_add_f32_e32 v146, v146, v152
	s_waitcnt lgkmcnt(3)
	v_mfma_f32_32x32x16_bf16 v[38:53], v[212:215], v[184:187], v[38:53]
	v_exp_f32_e32 v168, v168
	v_exp_f32_e32 v169, v169
	v_exp_f32_e32 v170, v170
	v_exp_f32_e32 v171, v171
	s_waitcnt lgkmcnt(2)
	v_mfma_f32_32x32x16_bf16 v[70:85], v[220:223], v[184:187], v[70:85]
	v_exp_f32_e32 v172, v172
	v_exp_f32_e32 v173, v173
	v_exp_f32_e32 v174, v174
	v_exp_f32_e32 v175, v175
	s_waitcnt lgkmcnt(1)
	v_mfma_f32_32x32x16_bf16 v[38:53], v[216:219], v[188:191], v[38:53]
	v_exp_f32_e32 v176, v176
	v_exp_f32_e32 v177, v177
	v_exp_f32_e32 v178, v178
	v_exp_f32_e32 v179, v179
	s_waitcnt lgkmcnt(0)
	v_mfma_f32_32x32x16_bf16 v[70:85], v[244:247], v[188:191], v[70:85]
	v_exp_f32_e32 v180, v180
	v_exp_f32_e32 v181, v181
	v_exp_f32_e32 v182, v182
	v_exp_f32_e32 v183, v183
	v_cvt_pk_bf16_f32 v184, v168, v169
	v_cvt_pk_bf16_f32 v185, v170, v171
	v_cvt_pk_bf16_f32 v186, v172, v173
	v_cvt_pk_bf16_f32 v187, v174, v175
	v_cvt_pk_bf16_f32 v188, v176, v177
	v_cvt_pk_bf16_f32 v189, v178, v179
	v_cvt_pk_bf16_f32 v190, v180, v181
	v_cvt_pk_bf16_f32 v191, v182, v183
	v_add_f32_e32 v168, v168, v169
	v_add_f32_e32 v170, v170, v171
	v_add_f32_e32 v172, v172, v173
	v_add_f32_e32 v174, v174, v175
	v_add_f32_e32 v176, v176, v177
	v_add_f32_e32 v178, v178, v179
	v_add_f32_e32 v180, v180, v181
	v_add_f32_e32 v182, v182, v183
	v_add_f32_e32 v168, v168, v170
	v_add_f32_e32 v172, v172, v174
	v_add_f32_e32 v176, v176, v178
	v_add_f32_e32 v180, v180, v182
	v_add_f32_e32 v168, v168, v172
	v_add_f32_e32 v176, v176, v180
	v_add_f32_e32 v168, v168, v176
	v_add_f32_e32 v147, v147, v168
	v_mfma_f32_32x32x16_bf16 v[54:69], v[212:215], v[184:187], v[54:69]
	s_and_b32 s12, s5, 64
	s_mulk_i32 s12, 0x90
	v_add_u32_e32 v192, s12, v230
	v_mfma_f32_32x32x16_bf16 v[86:101], v[220:223], v[184:187], v[86:101]
	v_lshl_add_u32 v193, v233, 1, v192
	v_lshl_add_u32 v194, v235, 1, v192
	s_waitcnt vmcnt(3)
	ds_write_b128 v193, v[102:105]
	v_mfma_f32_32x32x16_bf16 v[54:69], v[216:219], v[188:191], v[54:69]
	s_waitcnt vmcnt(2)
	ds_write_b128 v193, v[106:109] offset:18432
	s_waitcnt vmcnt(1)
	v_mfma_f32_32x32x16_bf16 v[86:101], v[244:247], v[188:191], v[86:101]
	ds_write_b128 v194, v[110:113]
	s_waitcnt vmcnt(0)
	ds_write_b128 v194, v[114:117] offset:18432
	s_cmp_eq_u32 s11, s5
	s_waitcnt lgkmcnt(0)
	s_barrier
	s_cbranch_scc0 .LBB0_943
	s_movk_i32 s12, 0x2400
	v_add_u32_e32 v148, s12, v237
	ds_read_b128 v[192:195], v148
	ds_read_b128 v[196:199], v148 offset:32
	ds_read_b128 v[200:203], v148 offset:64
	ds_read_b128 v[204:207], v148 offset:96
	s_addk_i32 s12, 0x4800
	v_add_u32_e32 v149, s12, v238
	s_addk_i32 s12, 0x1200
	v_add_u32_e32 v150, s12, v238
	s_waitcnt vmcnt(0)
	s_waitcnt lgkmcnt(3)
	v_mfma_f32_32x32x16_bf16 v[152:167], v[192:195], v[18:21], v[0:15]
	ds_read2_b64 v[212:215], v149 offset1:2
	s_waitcnt lgkmcnt(3)
	v_mfma_f32_32x32x16_bf16 v[152:167], v[196:199], v[22:25], v[152:167]
	ds_read2_b64 v[220:223], v150 offset1:2
	s_waitcnt lgkmcnt(3)
	v_mfma_f32_32x32x16_bf16 v[152:167], v[200:203], v[26:29], v[152:167]
	ds_read2_b64 v[216:219], v149 offset0:4 offset1:6
	s_waitcnt lgkmcnt(3)
	v_mfma_f32_32x32x16_bf16 v[152:167], v[204:207], v[30:33], v[152:167]
	ds_read2_b64 v[244:247], v150 offset0:4 offset1:6
	v_mfma_f32_32x32x16_bf16 v[168:183], v[192:195], v[34:37], v[0:15]
	ds_read_b128 v[192:195], v148 offset:4608
	v_mfma_f32_32x32x16_bf16 v[168:183], v[196:199], v[130:133], v[168:183]
	ds_read_b128 v[196:199], v148 offset:4640
	v_mfma_f32_32x32x16_bf16 v[168:183], v[200:203], v[134:137], v[168:183]
	ds_read_b128 v[200:203], v148 offset:4672
	v_mfma_f32_32x32x16_bf16 v[168:183], v[204:207], v[248:251], v[168:183]
	ds_read_b128 v[204:207], v148 offset:4704
	s_nop 0
	s_nop 0
	s_nop 0
	v_exp_f32_e32 v152, v152
	v_exp_f32_e32 v153, v153
	v_exp_f32_e32 v154, v154
	v_exp_f32_e32 v155, v155
	v_exp_f32_e32 v156, v156
	v_exp_f32_e32 v157, v157
	v_exp_f32_e32 v158, v158
	v_exp_f32_e32 v159, v159
	v_exp_f32_e32 v160, v160
	v_exp_f32_e32 v161, v161
	v_exp_f32_e32 v162, v162
	v_exp_f32_e32 v163, v163
	v_exp_f32_e32 v164, v164
	v_exp_f32_e32 v165, v165
	v_exp_f32_e32 v166, v166
	v_exp_f32_e32 v167, v167
	v_cvt_pk_bf16_f32 v184, v152, v153
	v_cvt_pk_bf16_f32 v185, v154, v155
	v_cvt_pk_bf16_f32 v186, v156, v157
	v_cvt_pk_bf16_f32 v187, v158, v159
	v_cvt_pk_bf16_f32 v188, v160, v161
	v_cvt_pk_bf16_f32 v189, v162, v163
	v_cvt_pk_bf16_f32 v190, v164, v165
	v_cvt_pk_bf16_f32 v191, v166, v167
	v_add_f32_e32 v152, v152, v153
	v_add_f32_e32 v154, v154, v155
	v_add_f32_e32 v156, v156, v157
	v_add_f32_e32 v158, v158, v159
	v_add_f32_e32 v160, v160, v161
	v_add_f32_e32 v162, v162, v163
	v_add_f32_e32 v164, v164, v165
	v_add_f32_e32 v166, v166, v167
	v_add_f32_e32 v152, v152, v154
	v_add_f32_e32 v156, v156, v158
	v_add_f32_e32 v160, v160, v162
	v_add_f32_e32 v164, v164, v166
	v_add_f32_e32 v152, v152, v156
	v_add_f32_e32 v160, v160, v164
	v_add_f32_e32 v152, v152, v160
	v_add_f32_e32 v146, v146, v152
	s_waitcnt lgkmcnt(7)
	v_mfma_f32_32x32x16_bf16 v[38:53], v[212:215], v[184:187], v[38:53]
	v_exp_f32_e32 v168, v168
	v_exp_f32_e32 v169, v169
	v_exp_f32_e32 v170, v170
	v_exp_f32_e32 v171, v171
	s_waitcnt lgkmcnt(6)
	v_mfma_f32_32x32x16_bf16 v[70:85], v[220:223], v[184:187], v[70:85]
	v_exp_f32_e32 v172, v172
	v_exp_f32_e32 v173, v173
	v_exp_f32_e32 v174, v174
	v_exp_f32_e32 v175, v175
	s_waitcnt lgkmcnt(5)
	v_mfma_f32_32x32x16_bf16 v[38:53], v[216:219], v[188:191], v[38:53]
	v_exp_f32_e32 v176, v176
	v_exp_f32_e32 v177, v177
	v_exp_f32_e32 v178, v178
	v_exp_f32_e32 v179, v179
	s_waitcnt lgkmcnt(4)
	v_mfma_f32_32x32x16_bf16 v[70:85], v[244:247], v[188:191], v[70:85]
	v_exp_f32_e32 v180, v180
	v_exp_f32_e32 v181, v181
	v_exp_f32_e32 v182, v182
	v_exp_f32_e32 v183, v183
	v_cvt_pk_bf16_f32 v184, v168, v169
	s_waitcnt lgkmcnt(3)
	v_mfma_f32_32x32x16_bf16 v[152:167], v[192:195], v[18:21], v[0:15]
	v_cvt_pk_bf16_f32 v185, v170, v171
	v_cvt_pk_bf16_f32 v186, v172, v173
	v_cvt_pk_bf16_f32 v187, v174, v175
	v_cvt_pk_bf16_f32 v188, v176, v177
	s_waitcnt lgkmcnt(2)
	v_mfma_f32_32x32x16_bf16 v[152:167], v[196:199], v[22:25], v[152:167]
	v_cvt_pk_bf16_f32 v189, v178, v179
	v_cvt_pk_bf16_f32 v190, v180, v181
	v_cvt_pk_bf16_f32 v191, v182, v183
	v_add_f32_e32 v168, v168, v169
	s_waitcnt lgkmcnt(1)
	v_mfma_f32_32x32x16_bf16 v[152:167], v[200:203], v[26:29], v[152:167]
	v_add_f32_e32 v170, v170, v171
	v_add_f32_e32 v172, v172, v173
	v_add_f32_e32 v174, v174, v175
	v_add_f32_e32 v176, v176, v177
	s_waitcnt lgkmcnt(0)
	v_mfma_f32_32x32x16_bf16 v[152:167], v[204:207], v[30:33], v[152:167]
	v_add_f32_e32 v178, v178, v179
	v_add_f32_e32 v180, v180, v181
	v_add_f32_e32 v182, v182, v183
	v_add_f32_e32 v168, v168, v170
	v_add_f32_e32 v172, v172, v174
	v_add_f32_e32 v176, v176, v178
	v_add_f32_e32 v180, v180, v182
	v_add_f32_e32 v168, v168, v172
	v_add_f32_e32 v176, v176, v180
	v_add_f32_e32 v168, v168, v176
	v_add_f32_e32 v147, v147, v168
	v_mfma_f32_32x32x16_bf16 v[54:69], v[212:215], v[184:187], v[54:69]
	ds_read2_b64 v[212:215], v149 offset0:8 offset1:10
	v_exp_f32_e32 v152, v152
	v_exp_f32_e32 v153, v153
	v_exp_f32_e32 v154, v154
	v_exp_f32_e32 v155, v155
	v_mfma_f32_32x32x16_bf16 v[86:101], v[220:223], v[184:187], v[86:101]
	ds_read2_b64 v[220:223], v150 offset0:8 offset1:10
	v_exp_f32_e32 v156, v156
	v_exp_f32_e32 v157, v157
	v_exp_f32_e32 v158, v158
	v_exp_f32_e32 v159, v159
	v_mfma_f32_32x32x16_bf16 v[54:69], v[216:219], v[188:191], v[54:69]
	ds_read2_b64 v[216:219], v149 offset0:12 offset1:14
	v_exp_f32_e32 v160, v160
	v_exp_f32_e32 v161, v161
	v_exp_f32_e32 v162, v162
	v_exp_f32_e32 v163, v163
	v_mfma_f32_32x32x16_bf16 v[86:101], v[244:247], v[188:191], v[86:101]
	ds_read2_b64 v[244:247], v150 offset0:12 offset1:14
	v_exp_f32_e32 v164, v164
	v_exp_f32_e32 v165, v165
	v_exp_f32_e32 v166, v166
	v_exp_f32_e32 v167, v167
	v_cvt_pk_bf16_f32 v184, v152, v153
	v_mfma_f32_32x32x16_bf16 v[168:183], v[192:195], v[34:37], v[0:15]
	v_cvt_pk_bf16_f32 v185, v154, v155
	v_cvt_pk_bf16_f32 v186, v156, v157
	v_cvt_pk_bf16_f32 v187, v158, v159
	v_cvt_pk_bf16_f32 v188, v160, v161
	v_mfma_f32_32x32x16_bf16 v[168:183], v[196:199], v[130:133], v[168:183]
	v_cvt_pk_bf16_f32 v189, v162, v163
	v_cvt_pk_bf16_f32 v190, v164, v165
	v_cvt_pk_bf16_f32 v191, v166, v167
	v_add_f32_e32 v152, v152, v153
	v_mfma_f32_32x32x16_bf16 v[168:183], v[200:203], v[134:137], v[168:183]
	v_add_f32_e32 v154, v154, v155
	v_add_f32_e32 v156, v156, v157
	v_add_f32_e32 v158, v158, v159
	v_add_f32_e32 v160, v160, v161
	v_mfma_f32_32x32x16_bf16 v[168:183], v[204:207], v[248:251], v[168:183]
	v_add_f32_e32 v162, v162, v163
	v_add_f32_e32 v164, v164, v165
	v_add_f32_e32 v166, v166, v167
	v_add_f32_e32 v152, v152, v154
	v_add_f32_e32 v156, v156, v158
	v_add_f32_e32 v160, v160, v162
	v_add_f32_e32 v164, v164, v166
	v_add_f32_e32 v152, v152, v156
	v_add_f32_e32 v160, v160, v164
	v_add_f32_e32 v152, v152, v160
	v_add_f32_e32 v146, v146, v152
	s_waitcnt lgkmcnt(3)
	v_mfma_f32_32x32x16_bf16 v[38:53], v[212:215], v[184:187], v[38:53]
	v_exp_f32_e32 v168, v168
	v_exp_f32_e32 v169, v169
	v_exp_f32_e32 v170, v170
	v_exp_f32_e32 v171, v171
	s_waitcnt lgkmcnt(2)
	v_mfma_f32_32x32x16_bf16 v[70:85], v[220:223], v[184:187], v[70:85]
	v_exp_f32_e32 v172, v172
	v_exp_f32_e32 v173, v173
	v_exp_f32_e32 v174, v174
	v_exp_f32_e32 v175, v175
	s_waitcnt lgkmcnt(1)
	v_mfma_f32_32x32x16_bf16 v[38:53], v[216:219], v[188:191], v[38:53]
	v_exp_f32_e32 v176, v176
	v_exp_f32_e32 v177, v177
	v_exp_f32_e32 v178, v178
	v_exp_f32_e32 v179, v179
	s_waitcnt lgkmcnt(0)
	v_mfma_f32_32x32x16_bf16 v[70:85], v[244:247], v[188:191], v[70:85]
	v_exp_f32_e32 v180, v180
	v_exp_f32_e32 v181, v181
	v_exp_f32_e32 v182, v182
	v_exp_f32_e32 v183, v183
	v_cvt_pk_bf16_f32 v184, v168, v169
	v_cvt_pk_bf16_f32 v185, v170, v171
	v_cvt_pk_bf16_f32 v186, v172, v173
	v_cvt_pk_bf16_f32 v187, v174, v175
	v_cvt_pk_bf16_f32 v188, v176, v177
	v_cvt_pk_bf16_f32 v189, v178, v179
	v_cvt_pk_bf16_f32 v190, v180, v181
	v_cvt_pk_bf16_f32 v191, v182, v183
	v_add_f32_e32 v168, v168, v169
	v_add_f32_e32 v170, v170, v171
	v_add_f32_e32 v172, v172, v173
	v_add_f32_e32 v174, v174, v175
	v_add_f32_e32 v176, v176, v177
	v_add_f32_e32 v178, v178, v179
	v_add_f32_e32 v180, v180, v181
	v_add_f32_e32 v182, v182, v183
	v_add_f32_e32 v168, v168, v170
	v_add_f32_e32 v172, v172, v174
	v_add_f32_e32 v176, v176, v178
	v_add_f32_e32 v180, v180, v182
	v_add_f32_e32 v168, v168, v172
	v_add_f32_e32 v176, v176, v180
	v_add_f32_e32 v168, v168, v176
	v_add_f32_e32 v147, v147, v168
	v_mfma_f32_32x32x16_bf16 v[54:69], v[212:215], v[184:187], v[54:69]
	v_mfma_f32_32x32x16_bf16 v[86:101], v[220:223], v[184:187], v[86:101]
	v_mfma_f32_32x32x16_bf16 v[54:69], v[216:219], v[188:191], v[54:69]
	v_mfma_f32_32x32x16_bf16 v[86:101], v[244:247], v[188:191], v[86:101]
	s_lshr_b32 s13, s6, 4
	s_lshl_b32 s13, s13, 8
	s_cmpk_lt_u32 s6, 0x400
	s_cselect_b32 s13, s13, 0x4000
	s_add_i32 s6, s6, s3
	s_lshl_b32 s52, s4, 1
	s_barrier
	v_add_u32_e32 v152, s13, v121
	v_or_b32_e32 v154, 32, v152
	v_ashrrev_i32_e32 v153, 31, v152
	v_ashrrev_i32_e32 v155, 31, v154
	v_lshlrev_b64 v[152:153], 11, v[152:153]
	v_lshlrev_b64 v[154:155], 11, v[154:155]
	v_lshl_add_u64 v[156:157], v[128:129], 0, s[52:53]
	v_lshl_add_u64 v[152:153], v[156:157], 0, v[152:153]
	v_lshl_add_u64 v[154:155], v[156:157], 0, v[154:155]
	global_load_dwordx2 v[160:161], v[152:153], off
	global_load_dwordx2 v[162:163], v[152:153], off offset:16
	global_load_dwordx2 v[164:165], v[152:153], off offset:32
	global_load_dwordx2 v[166:167], v[152:153], off offset:48
	global_load_dwordx2 v[168:169], v[152:153], off offset:64
	global_load_dwordx2 v[170:171], v[152:153], off offset:80
	global_load_dwordx2 v[172:173], v[152:153], off offset:96
	global_load_dwordx2 v[174:175], v[152:153], off offset:112
	global_load_dwordx2 v[176:177], v[154:155], off
	global_load_dwordx2 v[178:179], v[154:155], off offset:16
	global_load_dwordx2 v[180:181], v[154:155], off offset:32
	global_load_dwordx2 v[182:183], v[154:155], off offset:48
	global_load_dwordx2 v[184:185], v[154:155], off offset:64
	global_load_dwordx2 v[186:187], v[154:155], off offset:80
	global_load_dwordx2 v[188:189], v[154:155], off offset:96
	global_load_dwordx2 v[190:191], v[154:155], off offset:112
	v_mov_b32_e32 v194, v146
	s_nop 1
	v_permlane32_swap_b32_e32 v194, v146
	s_nop 1
	v_add_f32_e32 v196, v194, v146
	v_div_scale_f32 v198, s[14:15], v196, v196, 1.0
	v_rcp_f32_e32 v199, v198
	v_div_scale_f32 v200, vcc, 1.0, v196, 1.0
	v_fma_f32 v201, -v198, v199, 1.0
	v_fmac_f32_e32 v199, v201, v199
	v_mul_f32_e32 v202, v200, v199
	v_fma_f32 v203, -v198, v202, v200
	v_fmac_f32_e32 v202, v203, v199
	v_fma_f32 v198, -v198, v202, v200
	v_div_fmas_f32 v203, v198, v199, v202
	v_div_fixup_f32 v192, v203, v196, 1.0
	v_mov_b32_e32 v194, v147
	s_nop 1
	v_permlane32_swap_b32_e32 v194, v147
	s_nop 1
	v_add_f32_e32 v197, v194, v147
	v_div_scale_f32 v198, s[14:15], v197, v197, 1.0
	v_rcp_f32_e32 v199, v198
	v_div_scale_f32 v200, vcc, 1.0, v197, 1.0
	v_fma_f32 v201, -v198, v199, 1.0
	v_fmac_f32_e32 v199, v201, v199
	v_mul_f32_e32 v202, v200, v199
	v_fma_f32 v203, -v198, v202, v200
	v_fmac_f32_e32 v202, v203, v199
	v_fma_f32 v198, -v198, v202, v200
	v_div_fmas_f32 v203, v198, v199, v202
	v_div_fixup_f32 v193, v203, v197, 1.0
	s_waitcnt vmcnt(0)
	v_lshlrev_b32_e32 v204, 16, v160
	v_and_b32_e32 v205, 0xffff0000, v160
	v_lshlrev_b32_e32 v206, 16, v161
	v_and_b32_e32 v207, 0xffff0000, v161
	v_mul_f32_e32 v212, 0xbfb8aa3b, v204
	v_mul_f32_e32 v213, 0xbfb8aa3b, v205
	v_mul_f32_e32 v214, 0xbfb8aa3b, v206
	v_mul_f32_e32 v215, 0xbfb8aa3b, v207
	v_exp_f32_e32 v212, v212
	v_exp_f32_e32 v213, v213
	v_exp_f32_e32 v214, v214
	v_exp_f32_e32 v215, v215
	v_mul_f32_e32 v38, v38, v192
	v_mul_f32_e32 v39, v39, v192
	v_mul_f32_e32 v40, v40, v192
	v_mul_f32_e32 v41, v41, v192
	v_add_f32_e32 v212, 1.0, v212
	v_add_f32_e32 v213, 1.0, v213
	v_add_f32_e32 v214, 1.0, v214
	v_add_f32_e32 v215, 1.0, v215
	v_rcp_f32_e32 v212, v212
	v_rcp_f32_e32 v213, v213
	v_rcp_f32_e32 v214, v214
	v_rcp_f32_e32 v215, v215
	s_nop 0
	v_mul_f32_e32 v204, v204, v212
	v_mul_f32_e32 v205, v205, v213
	v_mul_f32_e32 v206, v206, v214
	v_mul_f32_e32 v207, v207, v215
	v_mul_f32_e32 v38, v38, v204
	v_mul_f32_e32 v39, v39, v205
	v_mul_f32_e32 v40, v40, v206
	v_mul_f32_e32 v41, v41, v207
	v_cvt_pk_bf16_f32 v160, v38, v39
	v_cvt_pk_bf16_f32 v161, v40, v41
	global_store_dwordx2 v[152:153], v[160:161], off
	v_lshlrev_b32_e32 v204, 16, v162
	v_and_b32_e32 v205, 0xffff0000, v162
	v_lshlrev_b32_e32 v206, 16, v163
	v_and_b32_e32 v207, 0xffff0000, v163
	v_mul_f32_e32 v212, 0xbfb8aa3b, v204
	v_mul_f32_e32 v213, 0xbfb8aa3b, v205
	v_mul_f32_e32 v214, 0xbfb8aa3b, v206
	v_mul_f32_e32 v215, 0xbfb8aa3b, v207
	v_exp_f32_e32 v212, v212
	v_exp_f32_e32 v213, v213
	v_exp_f32_e32 v214, v214
	v_exp_f32_e32 v215, v215
	v_mul_f32_e32 v42, v42, v192
	v_mul_f32_e32 v43, v43, v192
	v_mul_f32_e32 v44, v44, v192
	v_mul_f32_e32 v45, v45, v192
	v_add_f32_e32 v212, 1.0, v212
	v_add_f32_e32 v213, 1.0, v213
	v_add_f32_e32 v214, 1.0, v214
	v_add_f32_e32 v215, 1.0, v215
	v_rcp_f32_e32 v212, v212
	v_rcp_f32_e32 v213, v213
	v_rcp_f32_e32 v214, v214
	v_rcp_f32_e32 v215, v215
	s_nop 0
	v_mul_f32_e32 v204, v204, v212
	v_mul_f32_e32 v205, v205, v213
	v_mul_f32_e32 v206, v206, v214
	v_mul_f32_e32 v207, v207, v215
	v_mul_f32_e32 v42, v42, v204
	v_mul_f32_e32 v43, v43, v205
	v_mul_f32_e32 v44, v44, v206
	v_mul_f32_e32 v45, v45, v207
	v_cvt_pk_bf16_f32 v162, v42, v43
	v_cvt_pk_bf16_f32 v163, v44, v45
	global_store_dwordx2 v[152:153], v[162:163], off offset:16
	v_lshlrev_b32_e32 v204, 16, v164
	v_and_b32_e32 v205, 0xffff0000, v164
	v_lshlrev_b32_e32 v206, 16, v165
	v_and_b32_e32 v207, 0xffff0000, v165
	v_mul_f32_e32 v212, 0xbfb8aa3b, v204
	v_mul_f32_e32 v213, 0xbfb8aa3b, v205
	v_mul_f32_e32 v214, 0xbfb8aa3b, v206
	v_mul_f32_e32 v215, 0xbfb8aa3b, v207
	v_exp_f32_e32 v212, v212
	v_exp_f32_e32 v213, v213
	v_exp_f32_e32 v214, v214
	v_exp_f32_e32 v215, v215
	v_mul_f32_e32 v46, v46, v192
	v_mul_f32_e32 v47, v47, v192
	v_mul_f32_e32 v48, v48, v192
	v_mul_f32_e32 v49, v49, v192
	v_add_f32_e32 v212, 1.0, v212
	v_add_f32_e32 v213, 1.0, v213
	v_add_f32_e32 v214, 1.0, v214
	v_add_f32_e32 v215, 1.0, v215
	v_rcp_f32_e32 v212, v212
	v_rcp_f32_e32 v213, v213
	v_rcp_f32_e32 v214, v214
	v_rcp_f32_e32 v215, v215
	s_nop 0
	v_mul_f32_e32 v204, v204, v212
	v_mul_f32_e32 v205, v205, v213
	v_mul_f32_e32 v206, v206, v214
	v_mul_f32_e32 v207, v207, v215
	v_mul_f32_e32 v46, v46, v204
	v_mul_f32_e32 v47, v47, v205
	v_mul_f32_e32 v48, v48, v206
	v_mul_f32_e32 v49, v49, v207
	v_cvt_pk_bf16_f32 v164, v46, v47
	v_cvt_pk_bf16_f32 v165, v48, v49
	global_store_dwordx2 v[152:153], v[164:165], off offset:32
	v_lshlrev_b32_e32 v204, 16, v166
	v_and_b32_e32 v205, 0xffff0000, v166
	v_lshlrev_b32_e32 v206, 16, v167
	v_and_b32_e32 v207, 0xffff0000, v167
	v_mul_f32_e32 v212, 0xbfb8aa3b, v204
	v_mul_f32_e32 v213, 0xbfb8aa3b, v205
	v_mul_f32_e32 v214, 0xbfb8aa3b, v206
	v_mul_f32_e32 v215, 0xbfb8aa3b, v207
	v_exp_f32_e32 v212, v212
	v_exp_f32_e32 v213, v213
	v_exp_f32_e32 v214, v214
	v_exp_f32_e32 v215, v215
	v_mul_f32_e32 v50, v50, v192
	v_mul_f32_e32 v51, v51, v192
	v_mul_f32_e32 v52, v52, v192
	v_mul_f32_e32 v53, v53, v192
	v_add_f32_e32 v212, 1.0, v212
	v_add_f32_e32 v213, 1.0, v213
	v_add_f32_e32 v214, 1.0, v214
	v_add_f32_e32 v215, 1.0, v215
	v_rcp_f32_e32 v212, v212
	v_rcp_f32_e32 v213, v213
	v_rcp_f32_e32 v214, v214
	v_rcp_f32_e32 v215, v215
	s_nop 0
	v_mul_f32_e32 v204, v204, v212
	v_mul_f32_e32 v205, v205, v213
	v_mul_f32_e32 v206, v206, v214
	v_mul_f32_e32 v207, v207, v215
	v_mul_f32_e32 v50, v50, v204
	v_mul_f32_e32 v51, v51, v205
	v_mul_f32_e32 v52, v52, v206
	v_mul_f32_e32 v53, v53, v207
	v_cvt_pk_bf16_f32 v166, v50, v51
	v_cvt_pk_bf16_f32 v167, v52, v53
	global_store_dwordx2 v[152:153], v[166:167], off offset:48
	v_lshlrev_b32_e32 v204, 16, v168
	v_and_b32_e32 v205, 0xffff0000, v168
	v_lshlrev_b32_e32 v206, 16, v169
	v_and_b32_e32 v207, 0xffff0000, v169
	v_mul_f32_e32 v212, 0xbfb8aa3b, v204
	v_mul_f32_e32 v213, 0xbfb8aa3b, v205
	v_mul_f32_e32 v214, 0xbfb8aa3b, v206
	v_mul_f32_e32 v215, 0xbfb8aa3b, v207
	v_exp_f32_e32 v212, v212
	v_exp_f32_e32 v213, v213
	v_exp_f32_e32 v214, v214
	v_exp_f32_e32 v215, v215
	v_mul_f32_e32 v70, v70, v192
	v_mul_f32_e32 v71, v71, v192
	v_mul_f32_e32 v72, v72, v192
	v_mul_f32_e32 v73, v73, v192
	v_add_f32_e32 v212, 1.0, v212
	v_add_f32_e32 v213, 1.0, v213
	v_add_f32_e32 v214, 1.0, v214
	v_add_f32_e32 v215, 1.0, v215
	v_rcp_f32_e32 v212, v212
	v_rcp_f32_e32 v213, v213
	v_rcp_f32_e32 v214, v214
	v_rcp_f32_e32 v215, v215
	s_nop 0
	v_mul_f32_e32 v204, v204, v212
	v_mul_f32_e32 v205, v205, v213
	v_mul_f32_e32 v206, v206, v214
	v_mul_f32_e32 v207, v207, v215
	v_mul_f32_e32 v70, v70, v204
	v_mul_f32_e32 v71, v71, v205
	v_mul_f32_e32 v72, v72, v206
	v_mul_f32_e32 v73, v73, v207
	v_cvt_pk_bf16_f32 v168, v70, v71
	v_cvt_pk_bf16_f32 v169, v72, v73
	global_store_dwordx2 v[152:153], v[168:169], off offset:64
	v_lshlrev_b32_e32 v204, 16, v170
	v_and_b32_e32 v205, 0xffff0000, v170
	v_lshlrev_b32_e32 v206, 16, v171
	v_and_b32_e32 v207, 0xffff0000, v171
	v_mul_f32_e32 v212, 0xbfb8aa3b, v204
	v_mul_f32_e32 v213, 0xbfb8aa3b, v205
	v_mul_f32_e32 v214, 0xbfb8aa3b, v206
	v_mul_f32_e32 v215, 0xbfb8aa3b, v207
	v_exp_f32_e32 v212, v212
	v_exp_f32_e32 v213, v213
	v_exp_f32_e32 v214, v214
	v_exp_f32_e32 v215, v215
	v_mul_f32_e32 v74, v74, v192
	v_mul_f32_e32 v75, v75, v192
	v_mul_f32_e32 v76, v76, v192
	v_mul_f32_e32 v77, v77, v192
	v_add_f32_e32 v212, 1.0, v212
	v_add_f32_e32 v213, 1.0, v213
	v_add_f32_e32 v214, 1.0, v214
	v_add_f32_e32 v215, 1.0, v215
	v_rcp_f32_e32 v212, v212
	v_rcp_f32_e32 v213, v213
	v_rcp_f32_e32 v214, v214
	v_rcp_f32_e32 v215, v215
	s_nop 0
	v_mul_f32_e32 v204, v204, v212
	v_mul_f32_e32 v205, v205, v213
	v_mul_f32_e32 v206, v206, v214
	v_mul_f32_e32 v207, v207, v215
	v_mul_f32_e32 v74, v74, v204
	v_mul_f32_e32 v75, v75, v205
	v_mul_f32_e32 v76, v76, v206
	v_mul_f32_e32 v77, v77, v207
	v_cvt_pk_bf16_f32 v170, v74, v75
	v_cvt_pk_bf16_f32 v171, v76, v77
	global_store_dwordx2 v[152:153], v[170:171], off offset:80
	v_lshlrev_b32_e32 v204, 16, v172
	v_and_b32_e32 v205, 0xffff0000, v172
	v_lshlrev_b32_e32 v206, 16, v173
	v_and_b32_e32 v207, 0xffff0000, v173
	v_mul_f32_e32 v212, 0xbfb8aa3b, v204
	v_mul_f32_e32 v213, 0xbfb8aa3b, v205
	v_mul_f32_e32 v214, 0xbfb8aa3b, v206
	v_mul_f32_e32 v215, 0xbfb8aa3b, v207
	v_exp_f32_e32 v212, v212
	v_exp_f32_e32 v213, v213
	v_exp_f32_e32 v214, v214
	v_exp_f32_e32 v215, v215
	v_mul_f32_e32 v78, v78, v192
	v_mul_f32_e32 v79, v79, v192
	v_mul_f32_e32 v80, v80, v192
	v_mul_f32_e32 v81, v81, v192
	v_add_f32_e32 v212, 1.0, v212
	v_add_f32_e32 v213, 1.0, v213
	v_add_f32_e32 v214, 1.0, v214
	v_add_f32_e32 v215, 1.0, v215
	v_rcp_f32_e32 v212, v212
	v_rcp_f32_e32 v213, v213
	v_rcp_f32_e32 v214, v214
	v_rcp_f32_e32 v215, v215
	s_nop 0
	v_mul_f32_e32 v204, v204, v212
	v_mul_f32_e32 v205, v205, v213
	v_mul_f32_e32 v206, v206, v214
	v_mul_f32_e32 v207, v207, v215
	v_mul_f32_e32 v78, v78, v204
	v_mul_f32_e32 v79, v79, v205
	v_mul_f32_e32 v80, v80, v206
	v_mul_f32_e32 v81, v81, v207
	v_cvt_pk_bf16_f32 v172, v78, v79
	v_cvt_pk_bf16_f32 v173, v80, v81
	global_store_dwordx2 v[152:153], v[172:173], off offset:96
	v_lshlrev_b32_e32 v204, 16, v174
	v_and_b32_e32 v205, 0xffff0000, v174
	v_lshlrev_b32_e32 v206, 16, v175
	v_and_b32_e32 v207, 0xffff0000, v175
	v_mul_f32_e32 v212, 0xbfb8aa3b, v204
	v_mul_f32_e32 v213, 0xbfb8aa3b, v205
	v_mul_f32_e32 v214, 0xbfb8aa3b, v206
	v_mul_f32_e32 v215, 0xbfb8aa3b, v207
	v_exp_f32_e32 v212, v212
	v_exp_f32_e32 v213, v213
	v_exp_f32_e32 v214, v214
	v_exp_f32_e32 v215, v215
	v_mul_f32_e32 v82, v82, v192
	v_mul_f32_e32 v83, v83, v192
	v_mul_f32_e32 v84, v84, v192
	v_mul_f32_e32 v85, v85, v192
	v_add_f32_e32 v212, 1.0, v212
	v_add_f32_e32 v213, 1.0, v213
	v_add_f32_e32 v214, 1.0, v214
	v_add_f32_e32 v215, 1.0, v215
	v_rcp_f32_e32 v212, v212
	v_rcp_f32_e32 v213, v213
	v_rcp_f32_e32 v214, v214
	v_rcp_f32_e32 v215, v215
	s_nop 0
	v_mul_f32_e32 v204, v204, v212
	v_mul_f32_e32 v205, v205, v213
	v_mul_f32_e32 v206, v206, v214
	v_mul_f32_e32 v207, v207, v215
	v_mul_f32_e32 v82, v82, v204
	v_mul_f32_e32 v83, v83, v205
	v_mul_f32_e32 v84, v84, v206
	v_mul_f32_e32 v85, v85, v207
	v_cvt_pk_bf16_f32 v174, v82, v83
	v_cvt_pk_bf16_f32 v175, v84, v85
	global_store_dwordx2 v[152:153], v[174:175], off offset:112
	v_lshlrev_b32_e32 v204, 16, v176
	v_and_b32_e32 v205, 0xffff0000, v176
	v_lshlrev_b32_e32 v206, 16, v177
	v_and_b32_e32 v207, 0xffff0000, v177
	v_mul_f32_e32 v212, 0xbfb8aa3b, v204
	v_mul_f32_e32 v213, 0xbfb8aa3b, v205
	v_mul_f32_e32 v214, 0xbfb8aa3b, v206
	v_mul_f32_e32 v215, 0xbfb8aa3b, v207
	v_exp_f32_e32 v212, v212
	v_exp_f32_e32 v213, v213
	v_exp_f32_e32 v214, v214
	v_exp_f32_e32 v215, v215
	v_mul_f32_e32 v54, v54, v193
	v_mul_f32_e32 v55, v55, v193
	v_mul_f32_e32 v56, v56, v193
	v_mul_f32_e32 v57, v57, v193
	v_add_f32_e32 v212, 1.0, v212
	v_add_f32_e32 v213, 1.0, v213
	v_add_f32_e32 v214, 1.0, v214
	v_add_f32_e32 v215, 1.0, v215
	v_rcp_f32_e32 v212, v212
	v_rcp_f32_e32 v213, v213
	v_rcp_f32_e32 v214, v214
	v_rcp_f32_e32 v215, v215
	s_nop 0
	v_mul_f32_e32 v204, v204, v212
	v_mul_f32_e32 v205, v205, v213
	v_mul_f32_e32 v206, v206, v214
	v_mul_f32_e32 v207, v207, v215
	v_mul_f32_e32 v54, v54, v204
	v_mul_f32_e32 v55, v55, v205
	v_mul_f32_e32 v56, v56, v206
	v_mul_f32_e32 v57, v57, v207
	v_cvt_pk_bf16_f32 v176, v54, v55
	v_cvt_pk_bf16_f32 v177, v56, v57
	global_store_dwordx2 v[154:155], v[176:177], off
	v_lshlrev_b32_e32 v204, 16, v178
	v_and_b32_e32 v205, 0xffff0000, v178
	v_lshlrev_b32_e32 v206, 16, v179
	v_and_b32_e32 v207, 0xffff0000, v179
	v_mul_f32_e32 v212, 0xbfb8aa3b, v204
	v_mul_f32_e32 v213, 0xbfb8aa3b, v205
	v_mul_f32_e32 v214, 0xbfb8aa3b, v206
	v_mul_f32_e32 v215, 0xbfb8aa3b, v207
	v_exp_f32_e32 v212, v212
	v_exp_f32_e32 v213, v213
	v_exp_f32_e32 v214, v214
	v_exp_f32_e32 v215, v215
	v_mul_f32_e32 v58, v58, v193
	v_mul_f32_e32 v59, v59, v193
	v_mul_f32_e32 v60, v60, v193
	v_mul_f32_e32 v61, v61, v193
	v_add_f32_e32 v212, 1.0, v212
	v_add_f32_e32 v213, 1.0, v213
	v_add_f32_e32 v214, 1.0, v214
	v_add_f32_e32 v215, 1.0, v215
	v_rcp_f32_e32 v212, v212
	v_rcp_f32_e32 v213, v213
	v_rcp_f32_e32 v214, v214
	v_rcp_f32_e32 v215, v215
	s_nop 0
	v_mul_f32_e32 v204, v204, v212
	v_mul_f32_e32 v205, v205, v213
	v_mul_f32_e32 v206, v206, v214
	v_mul_f32_e32 v207, v207, v215
	v_mul_f32_e32 v58, v58, v204
	v_mul_f32_e32 v59, v59, v205
	v_mul_f32_e32 v60, v60, v206
	v_mul_f32_e32 v61, v61, v207
	v_cvt_pk_bf16_f32 v178, v58, v59
	v_cvt_pk_bf16_f32 v179, v60, v61
	global_store_dwordx2 v[154:155], v[178:179], off offset:16
	v_lshlrev_b32_e32 v204, 16, v180
	v_and_b32_e32 v205, 0xffff0000, v180
	v_lshlrev_b32_e32 v206, 16, v181
	v_and_b32_e32 v207, 0xffff0000, v181
	v_mul_f32_e32 v212, 0xbfb8aa3b, v204
	v_mul_f32_e32 v213, 0xbfb8aa3b, v205
	v_mul_f32_e32 v214, 0xbfb8aa3b, v206
	v_mul_f32_e32 v215, 0xbfb8aa3b, v207
	v_exp_f32_e32 v212, v212
	v_exp_f32_e32 v213, v213
	v_exp_f32_e32 v214, v214
	v_exp_f32_e32 v215, v215
	v_mul_f32_e32 v62, v62, v193
	v_mul_f32_e32 v63, v63, v193
	v_mul_f32_e32 v64, v64, v193
	v_mul_f32_e32 v65, v65, v193
	v_add_f32_e32 v212, 1.0, v212
	v_add_f32_e32 v213, 1.0, v213
	v_add_f32_e32 v214, 1.0, v214
	v_add_f32_e32 v215, 1.0, v215
	v_rcp_f32_e32 v212, v212
	v_rcp_f32_e32 v213, v213
	v_rcp_f32_e32 v214, v214
	v_rcp_f32_e32 v215, v215
	s_nop 0
	v_mul_f32_e32 v204, v204, v212
	v_mul_f32_e32 v205, v205, v213
	v_mul_f32_e32 v206, v206, v214
	v_mul_f32_e32 v207, v207, v215
	v_mul_f32_e32 v62, v62, v204
	v_mul_f32_e32 v63, v63, v205
	v_mul_f32_e32 v64, v64, v206
	v_mul_f32_e32 v65, v65, v207
	v_cvt_pk_bf16_f32 v180, v62, v63
	v_cvt_pk_bf16_f32 v181, v64, v65
	global_store_dwordx2 v[154:155], v[180:181], off offset:32
	v_lshlrev_b32_e32 v204, 16, v182
	v_and_b32_e32 v205, 0xffff0000, v182
	v_lshlrev_b32_e32 v206, 16, v183
	v_and_b32_e32 v207, 0xffff0000, v183
	v_mul_f32_e32 v212, 0xbfb8aa3b, v204
	v_mul_f32_e32 v213, 0xbfb8aa3b, v205
	v_mul_f32_e32 v214, 0xbfb8aa3b, v206
	v_mul_f32_e32 v215, 0xbfb8aa3b, v207
	v_exp_f32_e32 v212, v212
	v_exp_f32_e32 v213, v213
	v_exp_f32_e32 v214, v214
	v_exp_f32_e32 v215, v215
	v_mul_f32_e32 v66, v66, v193
	v_mul_f32_e32 v67, v67, v193
	v_mul_f32_e32 v68, v68, v193
	v_mul_f32_e32 v69, v69, v193
	v_add_f32_e32 v212, 1.0, v212
	v_add_f32_e32 v213, 1.0, v213
	v_add_f32_e32 v214, 1.0, v214
	v_add_f32_e32 v215, 1.0, v215
	v_rcp_f32_e32 v212, v212
	v_rcp_f32_e32 v213, v213
	v_rcp_f32_e32 v214, v214
	v_rcp_f32_e32 v215, v215
	s_nop 0
	v_mul_f32_e32 v204, v204, v212
	v_mul_f32_e32 v205, v205, v213
	v_mul_f32_e32 v206, v206, v214
	v_mul_f32_e32 v207, v207, v215
	v_mul_f32_e32 v66, v66, v204
	v_mul_f32_e32 v67, v67, v205
	v_mul_f32_e32 v68, v68, v206
	v_mul_f32_e32 v69, v69, v207
	v_cvt_pk_bf16_f32 v182, v66, v67
	v_cvt_pk_bf16_f32 v183, v68, v69
	global_store_dwordx2 v[154:155], v[182:183], off offset:48
	v_lshlrev_b32_e32 v204, 16, v184
	v_and_b32_e32 v205, 0xffff0000, v184
	v_lshlrev_b32_e32 v206, 16, v185
	v_and_b32_e32 v207, 0xffff0000, v185
	v_mul_f32_e32 v212, 0xbfb8aa3b, v204
	v_mul_f32_e32 v213, 0xbfb8aa3b, v205
	v_mul_f32_e32 v214, 0xbfb8aa3b, v206
	v_mul_f32_e32 v215, 0xbfb8aa3b, v207
	v_exp_f32_e32 v212, v212
	v_exp_f32_e32 v213, v213
	v_exp_f32_e32 v214, v214
	v_exp_f32_e32 v215, v215
	v_mul_f32_e32 v86, v86, v193
	v_mul_f32_e32 v87, v87, v193
	v_mul_f32_e32 v88, v88, v193
	v_mul_f32_e32 v89, v89, v193
	v_add_f32_e32 v212, 1.0, v212
	v_add_f32_e32 v213, 1.0, v213
	v_add_f32_e32 v214, 1.0, v214
	v_add_f32_e32 v215, 1.0, v215
	v_rcp_f32_e32 v212, v212
	v_rcp_f32_e32 v213, v213
	v_rcp_f32_e32 v214, v214
	v_rcp_f32_e32 v215, v215
	s_nop 0
	v_mul_f32_e32 v204, v204, v212
	v_mul_f32_e32 v205, v205, v213
	v_mul_f32_e32 v206, v206, v214
	v_mul_f32_e32 v207, v207, v215
	v_mul_f32_e32 v86, v86, v204
	v_mul_f32_e32 v87, v87, v205
	v_mul_f32_e32 v88, v88, v206
	v_mul_f32_e32 v89, v89, v207
	v_cvt_pk_bf16_f32 v184, v86, v87
	v_cvt_pk_bf16_f32 v185, v88, v89
	global_store_dwordx2 v[154:155], v[184:185], off offset:64
	v_lshlrev_b32_e32 v204, 16, v186
	v_and_b32_e32 v205, 0xffff0000, v186
	v_lshlrev_b32_e32 v206, 16, v187
	v_and_b32_e32 v207, 0xffff0000, v187
	v_mul_f32_e32 v212, 0xbfb8aa3b, v204
	v_mul_f32_e32 v213, 0xbfb8aa3b, v205
	v_mul_f32_e32 v214, 0xbfb8aa3b, v206
	v_mul_f32_e32 v215, 0xbfb8aa3b, v207
	v_exp_f32_e32 v212, v212
	v_exp_f32_e32 v213, v213
	v_exp_f32_e32 v214, v214
	v_exp_f32_e32 v215, v215
	v_mul_f32_e32 v90, v90, v193
	v_mul_f32_e32 v91, v91, v193
	v_mul_f32_e32 v92, v92, v193
	v_mul_f32_e32 v93, v93, v193
	v_add_f32_e32 v212, 1.0, v212
	v_add_f32_e32 v213, 1.0, v213
	v_add_f32_e32 v214, 1.0, v214
	v_add_f32_e32 v215, 1.0, v215
	v_rcp_f32_e32 v212, v212
	v_rcp_f32_e32 v213, v213
	v_rcp_f32_e32 v214, v214
	v_rcp_f32_e32 v215, v215
	s_nop 0
	v_mul_f32_e32 v204, v204, v212
	v_mul_f32_e32 v205, v205, v213
	v_mul_f32_e32 v206, v206, v214
	v_mul_f32_e32 v207, v207, v215
	v_mul_f32_e32 v90, v90, v204
	v_mul_f32_e32 v91, v91, v205
	v_mul_f32_e32 v92, v92, v206
	v_mul_f32_e32 v93, v93, v207
	v_cvt_pk_bf16_f32 v186, v90, v91
	v_cvt_pk_bf16_f32 v187, v92, v93
	global_store_dwordx2 v[154:155], v[186:187], off offset:80
	v_lshlrev_b32_e32 v204, 16, v188
	v_and_b32_e32 v205, 0xffff0000, v188
	v_lshlrev_b32_e32 v206, 16, v189
	v_and_b32_e32 v207, 0xffff0000, v189
	v_mul_f32_e32 v212, 0xbfb8aa3b, v204
	v_mul_f32_e32 v213, 0xbfb8aa3b, v205
	v_mul_f32_e32 v214, 0xbfb8aa3b, v206
	v_mul_f32_e32 v215, 0xbfb8aa3b, v207
	v_exp_f32_e32 v212, v212
	v_exp_f32_e32 v213, v213
	v_exp_f32_e32 v214, v214
	v_exp_f32_e32 v215, v215
	v_mul_f32_e32 v94, v94, v193
	v_mul_f32_e32 v95, v95, v193
	v_mul_f32_e32 v96, v96, v193
	v_mul_f32_e32 v97, v97, v193
	v_add_f32_e32 v212, 1.0, v212
	v_add_f32_e32 v213, 1.0, v213
	v_add_f32_e32 v214, 1.0, v214
	v_add_f32_e32 v215, 1.0, v215
	v_rcp_f32_e32 v212, v212
	v_rcp_f32_e32 v213, v213
	v_rcp_f32_e32 v214, v214
	v_rcp_f32_e32 v215, v215
	s_nop 0
	v_mul_f32_e32 v204, v204, v212
	v_mul_f32_e32 v205, v205, v213
	v_mul_f32_e32 v206, v206, v214
	v_mul_f32_e32 v207, v207, v215
	v_mul_f32_e32 v94, v94, v204
	v_mul_f32_e32 v95, v95, v205
	v_mul_f32_e32 v96, v96, v206
	v_mul_f32_e32 v97, v97, v207
	v_cvt_pk_bf16_f32 v188, v94, v95
	v_cvt_pk_bf16_f32 v189, v96, v97
	global_store_dwordx2 v[154:155], v[188:189], off offset:96
	v_lshlrev_b32_e32 v204, 16, v190
	v_and_b32_e32 v205, 0xffff0000, v190
	v_lshlrev_b32_e32 v206, 16, v191
	v_and_b32_e32 v207, 0xffff0000, v191
	v_mul_f32_e32 v212, 0xbfb8aa3b, v204
	v_mul_f32_e32 v213, 0xbfb8aa3b, v205
	v_mul_f32_e32 v214, 0xbfb8aa3b, v206
	v_mul_f32_e32 v215, 0xbfb8aa3b, v207
	v_exp_f32_e32 v212, v212
	v_exp_f32_e32 v213, v213
	v_exp_f32_e32 v214, v214
	v_exp_f32_e32 v215, v215
	v_mul_f32_e32 v98, v98, v193
	v_mul_f32_e32 v99, v99, v193
	v_mul_f32_e32 v100, v100, v193
	v_mul_f32_e32 v101, v101, v193
	v_add_f32_e32 v212, 1.0, v212
	v_add_f32_e32 v213, 1.0, v213
	v_add_f32_e32 v214, 1.0, v214
	v_add_f32_e32 v215, 1.0, v215
	v_rcp_f32_e32 v212, v212
	v_rcp_f32_e32 v213, v213
	v_rcp_f32_e32 v214, v214
	v_rcp_f32_e32 v215, v215
	s_nop 0
	v_mul_f32_e32 v204, v204, v212
	v_mul_f32_e32 v205, v205, v213
	v_mul_f32_e32 v206, v206, v214
	v_mul_f32_e32 v207, v207, v215
	v_mul_f32_e32 v98, v98, v204
	v_mul_f32_e32 v99, v99, v205
	v_mul_f32_e32 v100, v100, v206
	v_mul_f32_e32 v101, v101, v207
	v_cvt_pk_bf16_f32 v190, v98, v99
	v_cvt_pk_bf16_f32 v191, v100, v101
	global_store_dwordx2 v[154:155], v[190:191], off offset:112
	s_waitcnt vmcnt(0)
	s_cmpk_gt_i32 s6, 0x40f
	s_cbranch_scc0 .LBB0_937

.Lg_bf_epi:
	s_waitcnt vmcnt(0)
	v_add_u32_e32 v66, s11, v113
	v_add_u32_e32 v70, s29, v115
	s_lshl_b32 s98, s64, 1
	s_lshl_b32 s99, s64, 5
	v_mul_lo_u32 v72, v70, s98
	v_lshl_add_u32 v72, v66, 1, v72
	v_add_u32_e32 v73, s98, v72
	v_add_u32_e32 v74, s98, v73
	v_add_u32_e32 v75, s98, v74
	v_add_u32_e32 v76, s99, v72
	v_add_u32_e32 v77, s98, v76
	v_add_u32_e32 v78, s98, v77
	v_add_u32_e32 v79, s98, v78
	v_add_u32_e32 v80, s99, v76
	v_add_u32_e32 v81, s98, v80
	v_add_u32_e32 v82, s98, v81
	v_add_u32_e32 v83, s98, v82
	v_add_u32_e32 v84, s99, v80
	v_add_u32_e32 v85, s98, v84
	v_add_u32_e32 v86, s98, v85
	v_add_u32_e32 v87, s98, v86
	v_cvt_pk_bf16_f32 v88, v62, v63
	global_store_short v72, v88, s[48:49]
	global_store_short_d16_hi v73, v88, s[48:49]
	v_cvt_pk_bf16_f32 v89, v64, v65
	global_store_short v74, v89, s[48:49]
	global_store_short_d16_hi v75, v89, s[48:49]
	v_cvt_pk_bf16_f32 v90, v58, v59
	global_store_short v72, v90, s[48:49] offset:32
	global_store_short_d16_hi v73, v90, s[48:49] offset:32
	v_cvt_pk_bf16_f32 v91, v60, v61
	global_store_short v74, v91, s[48:49] offset:32
	global_store_short_d16_hi v75, v91, s[48:49] offset:32
	v_cvt_pk_bf16_f32 v92, v54, v55
	global_store_short v72, v92, s[48:49] offset:64
	global_store_short_d16_hi v73, v92, s[48:49] offset:64
	v_cvt_pk_bf16_f32 v93, v56, v57
	global_store_short v74, v93, s[48:49] offset:64
	global_store_short_d16_hi v75, v93, s[48:49] offset:64
	v_cvt_pk_bf16_f32 v94, v50, v51
	global_store_short v72, v94, s[48:49] offset:96
	global_store_short_d16_hi v73, v94, s[48:49] offset:96
	v_cvt_pk_bf16_f32 v95, v52, v53
	global_store_short v74, v95, s[48:49] offset:96
	global_store_short_d16_hi v75, v95, s[48:49] offset:96
	v_cvt_pk_bf16_f32 v88, v46, v47
	global_store_short v76, v88, s[48:49]
	global_store_short_d16_hi v77, v88, s[48:49]
	v_cvt_pk_bf16_f32 v89, v48, v49
	global_store_short v78, v89, s[48:49]
	global_store_short_d16_hi v79, v89, s[48:49]
	v_cvt_pk_bf16_f32 v90, v42, v43
	global_store_short v76, v90, s[48:49] offset:32
	global_store_short_d16_hi v77, v90, s[48:49] offset:32
	v_cvt_pk_bf16_f32 v91, v44, v45
	global_store_short v78, v91, s[48:49] offset:32
	global_store_short_d16_hi v79, v91, s[48:49] offset:32
	v_cvt_pk_bf16_f32 v92, v38, v39
	global_store_short v76, v92, s[48:49] offset:64
	global_store_short_d16_hi v77, v92, s[48:49] offset:64
	v_cvt_pk_bf16_f32 v93, v40, v41
	global_store_short v78, v93, s[48:49] offset:64
	global_store_short_d16_hi v79, v93, s[48:49] offset:64
	v_cvt_pk_bf16_f32 v94, v34, v35
	global_store_short v76, v94, s[48:49] offset:96
	global_store_short_d16_hi v77, v94, s[48:49] offset:96
	v_cvt_pk_bf16_f32 v95, v36, v37
	global_store_short v78, v95, s[48:49] offset:96
	global_store_short_d16_hi v79, v95, s[48:49] offset:96
	v_cvt_pk_bf16_f32 v88, v30, v31
	global_store_short v80, v88, s[48:49]
	global_store_short_d16_hi v81, v88, s[48:49]
	v_cvt_pk_bf16_f32 v89, v32, v33
	global_store_short v82, v89, s[48:49]
	global_store_short_d16_hi v83, v89, s[48:49]
	v_cvt_pk_bf16_f32 v90, v26, v27
	global_store_short v80, v90, s[48:49] offset:32
	global_store_short_d16_hi v81, v90, s[48:49] offset:32
	v_cvt_pk_bf16_f32 v91, v28, v29
	global_store_short v82, v91, s[48:49] offset:32
	global_store_short_d16_hi v83, v91, s[48:49] offset:32
	v_cvt_pk_bf16_f32 v92, v22, v23
	global_store_short v80, v92, s[48:49] offset:64
	global_store_short_d16_hi v81, v92, s[48:49] offset:64
	v_cvt_pk_bf16_f32 v93, v24, v25
	global_store_short v82, v93, s[48:49] offset:64
	global_store_short_d16_hi v83, v93, s[48:49] offset:64
	v_cvt_pk_bf16_f32 v94, v18, v19
	global_store_short v80, v94, s[48:49] offset:96
	global_store_short_d16_hi v81, v94, s[48:49] offset:96
	v_cvt_pk_bf16_f32 v95, v20, v21
	global_store_short v82, v95, s[48:49] offset:96
	global_store_short_d16_hi v83, v95, s[48:49] offset:96
	v_cvt_pk_bf16_f32 v88, v12, v13
	global_store_short v84, v88, s[48:49]
	global_store_short_d16_hi v85, v88, s[48:49]
	v_cvt_pk_bf16_f32 v89, v14, v15
	global_store_short v86, v89, s[48:49]
	global_store_short_d16_hi v87, v89, s[48:49]
	v_cvt_pk_bf16_f32 v90, v8, v9
	global_store_short v84, v90, s[48:49] offset:32
	global_store_short_d16_hi v85, v90, s[48:49] offset:32
	v_cvt_pk_bf16_f32 v91, v10, v11
	global_store_short v86, v91, s[48:49] offset:32
	global_store_short_d16_hi v87, v91, s[48:49] offset:32
	v_cvt_pk_bf16_f32 v92, v4, v5
	global_store_short v84, v92, s[48:49] offset:64
	global_store_short_d16_hi v85, v92, s[48:49] offset:64
	v_cvt_pk_bf16_f32 v93, v6, v7
	global_store_short v86, v93, s[48:49] offset:64
	global_store_short_d16_hi v87, v93, s[48:49] offset:64
	v_cvt_pk_bf16_f32 v94, v0, v1
	global_store_short v84, v94, s[48:49] offset:96
	global_store_short_d16_hi v85, v94, s[48:49] offset:96
	v_cvt_pk_bf16_f32 v95, v2, v3
	global_store_short v86, v95, s[48:49] offset:96
	global_store_short_d16_hi v87, v95, s[48:49] offset:96
	s_waitcnt vmcnt(0)
	s_branch .LBB0_1041

.LBB0_1080:
	s_and_b64 vcc, exec, s[36:37]
	s_cbranch_vccnz .Lg_bf_no
	s_cmp_eq_u64 s[34:35], 0
	s_cbranch_scc1 .Lg_bf_epi

.LBB0_1417:
	s_load_dwordx2 s[10:11], s[76:77], 0x0
	s_load_dwordx2 s[12:13], s[90:91], 0x0
	s_load_dwordx2 s[6:7], s[86:87], 0x0
	s_waitcnt vmcnt(0)
	v_or_b32_e32 v66, s63, v113
	v_add_u32_e32 v70, s29, v115
	s_cmp_gt_i32 s29, 0x3fff
	s_cselect_b32 s34, 0xffffc000, 0
	v_add_u32_e32 v70, s34, v70
	v_lshlrev_b32_e32 v66, 2, v66
	v_lshl_add_u32 v72, v70, 12, v66
	s_waitcnt lgkmcnt(0)
	s_cselect_b32 s4, s12, s10
	s_cselect_b32 s5, s13, s11
	s_cselect_b32 s8, s16, s6
	s_cselect_b32 s9, s17, s7
	s_cselect_b32 s34, s84, s82
	s_cselect_b32 s35, s85, s83
	global_load_dword v88, v66, s[34:35]
	global_load_dword v89, v66, s[34:35] offset:64
	global_load_dword v90, v66, s[34:35] offset:128
	global_load_dword v91, v66, s[34:35] offset:192
	global_load_dword v156, v72, s[4:5]
	global_load_dword v157, v72, s[4:5] offset:64
	global_load_dword v158, v72, s[4:5] offset:128
	global_load_dword v159, v72, s[4:5] offset:192
	v_add_u32_e32 v73, 0x1000, v72
	global_load_dword v160, v73, s[4:5]
	global_load_dword v161, v73, s[4:5] offset:64
	global_load_dword v162, v73, s[4:5] offset:128
	global_load_dword v163, v73, s[4:5] offset:192
	v_add_u32_e32 v74, 0x2000, v72
	global_load_dword v164, v74, s[4:5]
	global_load_dword v165, v74, s[4:5] offset:64
	global_load_dword v166, v74, s[4:5] offset:128
	global_load_dword v167, v74, s[4:5] offset:192
	v_add_u32_e32 v75, 0x3000, v72
	global_load_dword v168, v75, s[4:5]
	global_load_dword v169, v75, s[4:5] offset:64
	global_load_dword v170, v75, s[4:5] offset:128
	global_load_dword v171, v75, s[4:5] offset:192
	v_add_u32_e32 v76, 0x10000, v72
	global_load_dword v172, v76, s[4:5]
	global_load_dword v173, v76, s[4:5] offset:64
	global_load_dword v174, v76, s[4:5] offset:128
	global_load_dword v175, v76, s[4:5] offset:192
	v_add_u32_e32 v77, 0x11000, v72
	global_load_dword v176, v77, s[4:5]
	global_load_dword v177, v77, s[4:5] offset:64
	global_load_dword v178, v77, s[4:5] offset:128
	global_load_dword v179, v77, s[4:5] offset:192
	v_add_u32_e32 v78, 0x12000, v72
	global_load_dword v180, v78, s[4:5]
	global_load_dword v181, v78, s[4:5] offset:64
	global_load_dword v182, v78, s[4:5] offset:128
	global_load_dword v183, v78, s[4:5] offset:192
	v_add_u32_e32 v79, 0x13000, v72
	global_load_dword v184, v79, s[4:5]
	global_load_dword v185, v79, s[4:5] offset:64
	global_load_dword v186, v79, s[4:5] offset:128
	global_load_dword v187, v79, s[4:5] offset:192
	v_add_u32_e32 v80, 0x20000, v72
	global_load_dword v188, v80, s[4:5]
	global_load_dword v189, v80, s[4:5] offset:64
	global_load_dword v190, v80, s[4:5] offset:128
	global_load_dword v191, v80, s[4:5] offset:192
	v_add_u32_e32 v81, 0x21000, v72
	global_load_dword v192, v81, s[4:5]
	global_load_dword v193, v81, s[4:5] offset:64
	global_load_dword v194, v81, s[4:5] offset:128
	global_load_dword v195, v81, s[4:5] offset:192
	v_add_u32_e32 v82, 0x22000, v72
	global_load_dword v196, v82, s[4:5]
	global_load_dword v197, v82, s[4:5] offset:64
	global_load_dword v198, v82, s[4:5] offset:128
	global_load_dword v199, v82, s[4:5] offset:192
	v_add_u32_e32 v83, 0x23000, v72
	global_load_dword v200, v83, s[4:5]
	global_load_dword v201, v83, s[4:5] offset:64
	global_load_dword v202, v83, s[4:5] offset:128
	global_load_dword v203, v83, s[4:5] offset:192
	v_add_u32_e32 v84, 0x30000, v72
	global_load_dword v204, v84, s[4:5]
	global_load_dword v205, v84, s[4:5] offset:64
	global_load_dword v206, v84, s[4:5] offset:128
	global_load_dword v207, v84, s[4:5] offset:192
	v_add_u32_e32 v85, 0x31000, v72
	global_load_dword v212, v85, s[4:5]
	global_load_dword v213, v85, s[4:5] offset:64
	global_load_dword v214, v85, s[4:5] offset:128
	global_load_dword v215, v85, s[4:5] offset:192
	v_add_u32_e32 v86, 0x32000, v72
	global_load_dword v216, v86, s[4:5]
	global_load_dword v217, v86, s[4:5] offset:64
	global_load_dword v218, v86, s[4:5] offset:128
	global_load_dword v219, v86, s[4:5] offset:192
	v_add_u32_e32 v87, 0x33000, v72
	global_load_dword v220, v87, s[4:5]
	global_load_dword v221, v87, s[4:5] offset:64
	global_load_dword v222, v87, s[4:5] offset:128
	global_load_dword v223, v87, s[4:5] offset:192
	s_waitcnt vmcnt(0)
	v_fmac_f32_e32 v156, v62, v88
	v_fmac_f32_e32 v157, v58, v89
	v_fmac_f32_e32 v158, v54, v90
	v_fmac_f32_e32 v159, v50, v91
	v_fmac_f32_e32 v160, v63, v88
	v_fmac_f32_e32 v161, v59, v89
	v_fmac_f32_e32 v162, v55, v90
	v_fmac_f32_e32 v163, v51, v91
	v_fmac_f32_e32 v164, v64, v88
	v_fmac_f32_e32 v165, v60, v89
	v_fmac_f32_e32 v166, v56, v90
	v_fmac_f32_e32 v167, v52, v91
	v_fmac_f32_e32 v168, v65, v88
	v_fmac_f32_e32 v169, v61, v89
	v_fmac_f32_e32 v170, v57, v90
	v_fmac_f32_e32 v171, v53, v91
	v_fmac_f32_e32 v172, v46, v88
	v_fmac_f32_e32 v173, v42, v89
	v_fmac_f32_e32 v174, v38, v90
	v_fmac_f32_e32 v175, v34, v91
	v_fmac_f32_e32 v176, v47, v88
	v_fmac_f32_e32 v177, v43, v89
	v_fmac_f32_e32 v178, v39, v90
	v_fmac_f32_e32 v179, v35, v91
	v_fmac_f32_e32 v180, v48, v88
	v_fmac_f32_e32 v181, v44, v89
	v_fmac_f32_e32 v182, v40, v90
	v_fmac_f32_e32 v183, v36, v91
	v_fmac_f32_e32 v184, v49, v88
	v_fmac_f32_e32 v185, v45, v89
	v_fmac_f32_e32 v186, v41, v90
	v_fmac_f32_e32 v187, v37, v91
	v_fmac_f32_e32 v188, v30, v88
	v_fmac_f32_e32 v189, v26, v89
	v_fmac_f32_e32 v190, v22, v90
	v_fmac_f32_e32 v191, v18, v91
	v_fmac_f32_e32 v192, v31, v88
	v_fmac_f32_e32 v193, v27, v89
	v_fmac_f32_e32 v194, v23, v90
	v_fmac_f32_e32 v195, v19, v91
	v_fmac_f32_e32 v196, v32, v88
	v_fmac_f32_e32 v197, v28, v89
	v_fmac_f32_e32 v198, v24, v90
	v_fmac_f32_e32 v199, v20, v91
	v_fmac_f32_e32 v200, v33, v88
	v_fmac_f32_e32 v201, v29, v89
	v_fmac_f32_e32 v202, v25, v90
	v_fmac_f32_e32 v203, v21, v91
	v_fmac_f32_e32 v204, v12, v88
	v_fmac_f32_e32 v205, v8, v89
	v_fmac_f32_e32 v206, v4, v90
	v_fmac_f32_e32 v207, v0, v91
	v_fmac_f32_e32 v212, v13, v88
	v_fmac_f32_e32 v213, v9, v89
	v_fmac_f32_e32 v214, v5, v90
	v_fmac_f32_e32 v215, v1, v91
	v_fmac_f32_e32 v216, v14, v88
	v_fmac_f32_e32 v217, v10, v89
	v_fmac_f32_e32 v218, v6, v90
	v_fmac_f32_e32 v219, v2, v91
	v_fmac_f32_e32 v220, v15, v88
	v_fmac_f32_e32 v221, v11, v89
	v_fmac_f32_e32 v222, v7, v90
	v_fmac_f32_e32 v223, v3, v91
	global_store_dword v72, v156, s[8:9]
	global_store_dword v72, v157, s[8:9] offset:64
	global_store_dword v72, v158, s[8:9] offset:128
	global_store_dword v72, v159, s[8:9] offset:192
	global_store_dword v73, v160, s[8:9]
	global_store_dword v73, v161, s[8:9] offset:64
	global_store_dword v73, v162, s[8:9] offset:128
	global_store_dword v73, v163, s[8:9] offset:192
	global_store_dword v74, v164, s[8:9]
	global_store_dword v74, v165, s[8:9] offset:64
	global_store_dword v74, v166, s[8:9] offset:128
	global_store_dword v74, v167, s[8:9] offset:192
	global_store_dword v75, v168, s[8:9]
	global_store_dword v75, v169, s[8:9] offset:64
	global_store_dword v75, v170, s[8:9] offset:128
	global_store_dword v75, v171, s[8:9] offset:192
	global_store_dword v76, v172, s[8:9]
	global_store_dword v76, v173, s[8:9] offset:64
	global_store_dword v76, v174, s[8:9] offset:128
	global_store_dword v76, v175, s[8:9] offset:192
	global_store_dword v77, v176, s[8:9]
	global_store_dword v77, v177, s[8:9] offset:64
	global_store_dword v77, v178, s[8:9] offset:128
	global_store_dword v77, v179, s[8:9] offset:192
	global_store_dword v78, v180, s[8:9]
	global_store_dword v78, v181, s[8:9] offset:64
	global_store_dword v78, v182, s[8:9] offset:128
	global_store_dword v78, v183, s[8:9] offset:192
	global_store_dword v79, v184, s[8:9]
	global_store_dword v79, v185, s[8:9] offset:64
	global_store_dword v79, v186, s[8:9] offset:128
	global_store_dword v79, v187, s[8:9] offset:192
	global_store_dword v80, v188, s[8:9]
	global_store_dword v80, v189, s[8:9] offset:64
	global_store_dword v80, v190, s[8:9] offset:128
	global_store_dword v80, v191, s[8:9] offset:192
	global_store_dword v81, v192, s[8:9]
	global_store_dword v81, v193, s[8:9] offset:64
	global_store_dword v81, v194, s[8:9] offset:128
	global_store_dword v81, v195, s[8:9] offset:192
	global_store_dword v82, v196, s[8:9]
	global_store_dword v82, v197, s[8:9] offset:64
	global_store_dword v82, v198, s[8:9] offset:128
	global_store_dword v82, v199, s[8:9] offset:192
	global_store_dword v83, v200, s[8:9]
	global_store_dword v83, v201, s[8:9] offset:64
	global_store_dword v83, v202, s[8:9] offset:128
	global_store_dword v83, v203, s[8:9] offset:192
	global_store_dword v84, v204, s[8:9]
	global_store_dword v84, v205, s[8:9] offset:64
	global_store_dword v84, v206, s[8:9] offset:128
	global_store_dword v84, v207, s[8:9] offset:192
	global_store_dword v85, v212, s[8:9]
	global_store_dword v85, v213, s[8:9] offset:64
	global_store_dword v85, v214, s[8:9] offset:128
	global_store_dword v85, v215, s[8:9] offset:192
	global_store_dword v86, v216, s[8:9]
	global_store_dword v86, v217, s[8:9] offset:64
	global_store_dword v86, v218, s[8:9] offset:128
	global_store_dword v86, v219, s[8:9] offset:192
	global_store_dword v87, v220, s[8:9]
	global_store_dword v87, v221, s[8:9] offset:64
	global_store_dword v87, v222, s[8:9] offset:128
	global_store_dword v87, v223, s[8:9] offset:192
	s_waitcnt vmcnt(0)
	s_mov_b64 s[4:5], exec
	s_branch .LBB0_1040
